# nt5: nt4 plus nt on out-phase, final-norm, attention Q and gemm2/gemm4 epilogue X loads (all once-read)
# baseline (speedup 1.0000x reference)
; __device__ __forceinline__ void attn_phase(const Frame& F0, const Args& a0, int l, int u0, int ustride, int ucount, int ulimit, int uextra, bool last) {
;     ...
;         int hq, qb, kvh, b; bool isctx;
;         if (u < 512) { hq = u & 3; qb = (u >> 2) & 15; kvh = (u >> 6) & 1; b = u >> 7; isctx = false; }
;         else { const int uc = u - 512; hq = uc & 3; qb = (uc >> 2) & 1; kvh = (uc >> 3) & 1; b = uc >> 4; isctx = true; }
;         const int head = kvh * 4 + hq;
;         const int qrow0 = b * TT + (isctx ? qb * 128 : CTXL + qb * 128);
;         const int firstb = isctx ? 0 : (qb > 0 ? qb - 1 : 0), lastb = isctx ? -1 : (qb < 15 ? qb + 1 : 15);
;         const int nloc = isctx ? 0 : (lastb - firstb + 1) * 2, NT = nloc + 4;
;         bf16x8 Qf[4];
;         { const bf16* qp = Z + (size_t)(qrow0 + 16 * wave + c) * ZP + head * 128 + 8 * g;
; #pragma unroll
;           for (int kb = 0; kb < 4; ++kb) Qf[kb] = *(const bf16x8*)(qp + 32 * kb); }
;         float m = sink[head] * 1.4426950408889634f, lsum = (g == 0) ? 1.f : 0.f;
.LBB0_593:
	s_and_b32 s13, s19, 1
	s_and_b32 s12, s14, 3
	s_lshl_b32 s14, s13, 2
	s_or_b32 s14, s14, s12
	s_mul_i32 s12, s17, 0x900
	s_lshl_b32 s17, s15, 7
	s_add_i32 s19, s17, 0x100
	s_and_b64 s[22:23], exec, s[10:11]
	v_sub_u32_e64 v0, s15, 1 clamp
	s_cselect_b32 s24, s17, s19
	v_readfirstlane_b32 s17, v0
	s_cselect_b32 s17, 0, s17
	s_add_i32 s19, s15, 1
	s_cmp_lg_u32 s15, 15
	s_cselect_b32 s19, s19, 15
	s_and_b64 s[22:23], exec, s[10:11]
	s_cselect_b32 s19, -1, s19
	s_sub_i32 s19, s19, s17
	s_lshl_b32 s19, s19, 1
	s_add_i32 s19, s19, 2
	s_and_b64 s[10:11], exec, s[10:11]
	s_cselect_b32 s19, 0, s19
	s_add_i32 s24, s24, s12
	v_add_u32_e32 v148, s24, v154
	v_mov_b64_e32 v[0:1], s[4:5]
	v_mad_i64_i32 v[0:1], s[10:11], v148, s87, v[0:1]
	s_lshl_b32 s84, s14, 8
	v_lshl_add_u64 v[0:1], v[0:1], 0, s[84:85]
	v_lshl_add_u64 v[0:1], v[146:147], 1, v[0:1]
	global_load_dwordx4 v[20:23], v[0:1], off nt
	global_load_dwordx4 v[24:27], v[0:1], off offset:64 nt
	global_load_dwordx4 v[28:31], v[0:1], off offset:128 nt
	global_load_dwordx4 v[32:35], v[0:1], off offset:192 nt
	s_lshl_b32 s10, s14, 2
	v_mov_b32_e32 v0, s10
	global_load_dword v64, v0, s[8:9]
	s_cmp_lt_i32 s19, 1
	s_mov_b64 s[10:11], -1
	s_cbranch_scc0 .LBB0_595
	s_lshl_b32 s10, s19, 6
	s_sub_i32 s22, s12, s10
	s_mov_b64 s[10:11], 0

; __device__ __forceinline__ void attn_phase(const Frame& F0, const Args& a0, int l, int u0, int ustride, int ucount, int ulimit, int uextra, bool last) {
;     ...
;         int hq, qb, kvh, b; bool isctx;
;         if (u < 512) { hq = u & 3; qb = (u >> 2) & 15; kvh = (u >> 6) & 1; b = u >> 7; isctx = false; }
;         else { const int uc = u - 512; hq = uc & 3; qb = (uc >> 2) & 1; kvh = (uc >> 3) & 1; b = uc >> 4; isctx = true; }
;         const int head = kvh * 4 + hq;
;         const int qrow0 = b * TT + (isctx ? qb * 128 : CTXL + qb * 128);
;         const int firstb = isctx ? 0 : (qb > 0 ? qb - 1 : 0), lastb = isctx ? -1 : (qb < 15 ? qb + 1 : 15);
;         const int nloc = isctx ? 0 : (lastb - firstb + 1) * 2, NT = nloc + 4;
;         bf16x8 Qf[4];
;         { const bf16* qp = Z + (size_t)(qrow0 + 16 * wave + c) * ZP + head * 128 + 8 * g;
; #pragma unroll
;           for (int kb = 0; kb < 4; ++kb) Qf[kb] = *(const bf16x8*)(qp + 32 * kb); }
.LBB0_630:
	s_and_b32 s11, s18, 1
	s_and_b32 s10, s13, 3
	s_lshl_b32 s13, s11, 2
	s_or_b32 s13, s13, s10
	s_mul_i32 s10, s15, 0x900
	s_lshl_b32 s15, s14, 7
	s_add_i32 s22, s15, 0x100
	s_and_b64 s[18:19], exec, s[8:9]
	v_sub_u32_e64 v0, s14, 1 clamp
	s_cselect_b32 s22, s15, s22
	v_readfirstlane_b32 s15, v0
	s_cselect_b32 s15, 0, s15
	s_add_i32 s18, s14, 1
	s_cmp_lg_u32 s14, 15
	s_cselect_b32 s23, s18, 15
	s_and_b64 s[18:19], exec, s[8:9]
	s_cselect_b32 s18, -1, s23
	s_sub_i32 s18, s18, s15
	s_lshl_b32 s18, s18, 1
	s_add_i32 s18, s18, 2
	s_and_b64 s[8:9], exec, s[8:9]
	s_cselect_b32 s18, 0, s18
	s_add_i32 s22, s22, s10
	v_add_u32_e32 v148, s22, v154
	v_mov_b64_e32 v[0:1], s[4:5]
	v_mad_i64_i32 v[0:1], s[8:9], v148, s87, v[0:1]
	s_lshl_b32 s84, s13, 8
	v_lshl_add_u64 v[0:1], v[0:1], 0, s[84:85]
	v_lshl_add_u64 v[0:1], v[146:147], 1, v[0:1]
	global_load_dwordx4 v[20:23], v[0:1], off nt
	global_load_dwordx4 v[24:27], v[0:1], off offset:64 nt
	global_load_dwordx4 v[28:31], v[0:1], off offset:128 nt
	global_load_dwordx4 v[32:35], v[0:1], off offset:192 nt
	s_lshl_b32 s8, s13, 2
	v_mov_b32_e32 v0, s8
	global_load_dword v64, v0, s[0:1]
	s_cmp_lt_i32 s18, 1
	s_mov_b64 s[8:9], -1
	s_cbranch_scc0 .LBB0_632
	s_lshl_b32 s8, s18, 6
	s_sub_i32 s19, s10, s8
	s_mov_b64 s[8:9], 0

; __device__ __forceinline__ unsigned pk2(float lo, float hi) { return __builtin_bit_cast(unsigned, __builtin_convertvector((f32x2p){lo, hi}, bf16x2p)); }
; __device__ __forceinline__ float shx(float v, int m, int lane) { return __builtin_bit_cast(float, __builtin_amdgcn_ds_bpermute((lane ^ m) << 2, __builtin_bit_cast(int, v))); }
; __device__ __forceinline__ float siluf(float v) { return v / (1.f + __expf(-v)); }
; __device__ __forceinline__ void gdn_out_phase(const Frame& F0, const Args& a0, int l, bool last) {
;     ...
;     for (int m = gw; m < M; m += NGW) {
;         if (last && (m % TT) < CTXL) continue;
;         v2u oa[4], ob[4], gz[4];
; #pragma unroll
;         for (int k = 0; k < 4; ++k) { const int ch = (F.lane + 64 * k) * 4;
;             oa[k] = *(const v2u*)(GO + (size_t)m * 1024 + ch); ob[k] = *(const v2u*)(GO + (size_t)M * 1024 + (size_t)m * 1024 + ch); gz[k] = *(const v2u*)(Z + (size_t)m * ZP + OFF_GATE + ch); }
;         __builtin_amdgcn_sched_barrier(0);
; #pragma unroll
;         for (int k = 0; k < 4; ++k) { const int ch = (F.lane + 64 * k) * 4;
;             const f32x4 o = (f32x4){bflo(oa[k].x) + bflo(ob[k].x), bfhi(oa[k].x) + bfhi(ob[k].x), bflo(oa[k].y) + bflo(ob[k].y), bfhi(oa[k].y) + bfhi(ob[k].y)};
;             float ss = (o.x * o.x + o.y * o.y) + (o.z * o.z + o.w * o.w);
; #pragma unroll
;             for (int q = 1; q < 32; q <<= 1) ss += shx(ss, q, F.lane);
;             const float rn = 1.0f / sqrtf(ss * (1.f / 128.f) + EPS);
;             const float g0 = bflo(gz[k].x), g1 = bfhi(gz[k].x), g2 = bflo(gz[k].y), g3 = bfhi(gz[k].y);
;             v2u w; w.x = pk2(o.x * rn * gn[k].x * siluf(g0), o.y * rn * gn[k].y * siluf(g1));
;             w.y = pk2(o.z * rn * gn[k].z * siluf(g2), o.w * rn * gn[k].w * siluf(g3));
;             *(v2u*)(MIX + (size_t)m * 2048 + 1024 + ch) = w; }
.LBB0_742:
	s_mul_hi_i32 s2, s6, 0x38e38e39
	s_lshr_b32 s3, s2, 31
	s_ashr_i32 s2, s2, 9
	s_add_i32 s2, s2, s3
	s_mulk_i32 s2, 0x900
	s_sub_i32 s2, s6, s2
	s_cmpk_lt_i32 s2, 0x100
	s_cselect_b64 s[2:3], -1, 0
	s_and_b64 s[2:3], s[76:77], s[2:3]
	s_and_b64 vcc, exec, s[2:3]
	s_cbranch_vccnz .LBB0_741
	v_lshl_add_u64 v[22:23], s[4:5], 0, v[20:21]
	v_add_co_u32_e32 v24, vcc, 0x4b800000, v22
	v_lshl_add_u64 v[28:29], s[4:5], 0, v[18:19]
	s_nop 0
	v_addc_co_u32_e32 v25, vcc, 0, v23, vcc
	v_add_co_u32_e32 v22, vcc, 0x4ca00000, v22
	v_lshl_add_u64 v[34:35], s[4:5], 0, v[16:17]
	s_nop 0
	v_addc_co_u32_e32 v23, vcc, 0, v23, vcc
	global_load_dwordx2 v[42:43], v[24:25], off nt
	global_load_dwordx2 v[36:37], v[24:25], off offset:512 nt
	global_load_dwordx2 v[30:31], v[24:25], off offset:1024 nt
	s_nop 0
	global_load_dwordx2 v[24:25], v[24:25], off offset:1536 nt
	s_nop 0
	global_load_dwordx2 v[50:51], v[22:23], off nt
	global_load_dwordx2 v[38:39], v[22:23], off offset:512 nt
	global_load_dwordx2 v[32:33], v[22:23], off offset:1024 nt
	global_load_dwordx2 v[26:27], v[22:23], off offset:1536 nt
	v_lshl_add_u64 v[22:23], s[4:5], 0, v[12:13]
	v_lshl_add_u64 v[40:41], s[4:5], 0, v[14:15]
	global_load_dwordx2 v[52:53], v[28:29], off nt
	s_nop 0
	global_load_dwordx2 v[34:35], v[34:35], off nt
	s_nop 0
	global_load_dwordx2 v[28:29], v[40:41], off nt
	s_nop 0
	global_load_dwordx2 v[22:23], v[22:23], off nt
	s_waitcnt vmcnt(11)
	v_lshlrev_b32_e32 v40, 16, v43
	v_and_b32_e32 v41, 0xffff0000, v43
	s_waitcnt vmcnt(7)
	v_lshlrev_b32_e32 v54, 16, v51
	v_and_b32_e32 v55, 0xffff0000, v51
	v_pk_add_f32 v[40:41], v[40:41], v[54:55]
	v_lshlrev_b32_e32 v54, 16, v42
	v_and_b32_e32 v55, 0xffff0000, v42
	v_lshlrev_b32_e32 v42, 16, v50
	v_and_b32_e32 v43, 0xffff0000, v50
	v_pk_add_f32 v[42:43], v[54:55], v[42:43]
	v_mov_b32_e32 v55, v41
	v_mov_b32_e32 v54, v43
	v_mov_b32_e32 v50, v42
	v_mov_b32_e32 v51, v40
	v_pk_mul_f32 v[54:55], v[54:55], v[54:55]
	s_waitcnt vmcnt(3)
	v_lshlrev_b32_e32 v49, 16, v53
	v_pk_fma_f32 v[50:51], v[50:51], v[50:51], v[54:55]
	v_lshlrev_b32_e32 v54, 16, v52
	v_add_f32_e32 v50, v50, v51
	ds_bpermute_b32 v51, v44, v50
	v_and_b32_e32 v55, 0xffff0000, v52
	v_and_b32_e32 v56, 0xffff0000, v53
	v_mul_f32_e32 v52, 0xbfb8aa3b, v54
	v_mul_f32_e32 v53, 0xbfb8aa3b, v55
	v_exp_f32_e32 v52, v52
	v_exp_f32_e32 v53, v53
	s_waitcnt lgkmcnt(0)
	v_add_f32_e32 v50, v50, v51
	ds_bpermute_b32 v51, v45, v50
	v_pk_add_f32 v[52:53], v[52:53], 1.0 op_sel_hi:[1,0]
	s_nop 0
	v_div_scale_f32 v57, s[2:3], v53, v53, v55
	v_rcp_f32_e32 v58, v57
	s_waitcnt lgkmcnt(0)
	v_add_f32_e32 v50, v50, v51
	ds_bpermute_b32 v51, v46, v50
	v_fma_f32 v59, -v57, v58, 1.0
	v_fmac_f32_e32 v58, v59, v58
	v_div_scale_f32 v59, vcc, v55, v53, v55
	v_mul_f32_e32 v60, v59, v58
	v_fma_f32 v61, -v57, v60, v59
	v_fmac_f32_e32 v60, v61, v58
	s_waitcnt lgkmcnt(0)
	v_add_f32_e32 v50, v50, v51
	v_fma_f32 v57, -v57, v60, v59
	ds_bpermute_b32 v51, v47, v50
	v_div_fmas_f32 v57, v57, v58, v60
	v_div_fixup_f32 v53, v57, v53, v55
	v_div_scale_f32 v55, s[2:3], v52, v52, v54
	v_rcp_f32_e32 v57, v55
	s_waitcnt lgkmcnt(0)
	v_add_f32_e32 v50, v50, v51
	ds_bpermute_b32 v51, v48, v50
	v_fma_f32 v58, -v55, v57, 1.0
	v_fmac_f32_e32 v57, v58, v57
	v_div_scale_f32 v58, vcc, v54, v52, v54
	v_mul_f32_e32 v59, v58, v57
	v_fma_f32 v60, -v55, v59, v58
	v_fmac_f32_e32 v59, v60, v57
	s_waitcnt lgkmcnt(0)
	v_add_f32_e32 v50, v50, v51
	v_fma_f32 v55, -v55, v59, v58
	v_fmamk_f32 v50, v50, 0x3c000000, v182
	v_div_fmas_f32 v55, v55, v57, v59
	v_cmp_gt_f32_e32 vcc, s74, v50
	v_mul_f32_e32 v51, 0x4f800000, v50
	v_div_fixup_f32 v52, v55, v52, v54
	v_cndmask_b32_e32 v50, v50, v51, vcc
	v_sqrt_f32_e32 v51, v50
	s_nop 0
	v_add_u32_e32 v54, -1, v51
	v_fma_f32 v55, -v54, v51, v50
	v_cmp_ge_f32_e64 s[2:3], 0, v55
	v_add_u32_e32 v55, 1, v51
	s_nop 0
	v_cndmask_b32_e64 v54, v51, v54, s[2:3]
	v_fma_f32 v51, -v55, v51, v50
	v_cmp_lt_f32_e64 s[2:3], 0, v51
	s_nop 1
	v_cndmask_b32_e64 v51, v54, v55, s[2:3]
	v_mul_f32_e32 v54, 0x37800000, v51
	v_cndmask_b32_e32 v51, v51, v54, vcc
	v_cmp_class_f32_e32 vcc, v50, v183
	s_nop 1
	v_cndmask_b32_e32 v50, v51, v50, vcc
	v_div_scale_f32 v51, s[2:3], v50, v50, 1.0
	v_rcp_f32_e32 v54, v51
	s_nop 0
	v_fma_f32 v55, -v51, v54, 1.0
	v_fmac_f32_e32 v54, v55, v54
	v_div_scale_f32 v55, vcc, 1.0, v50, 1.0
	v_mul_f32_e32 v57, v55, v54
	v_fma_f32 v58, -v51, v57, v55
	v_fmac_f32_e32 v57, v58, v54
	v_fma_f32 v51, -v51, v57, v55
	v_div_fmas_f32 v51, v51, v54, v57
	v_div_fixup_f32 v50, v51, v50, 1.0
	v_pk_mul_f32 v[42:43], v[42:43], v[50:51] op_sel_hi:[1,0]
	v_pk_mul_f32 v[40:41], v[40:41], v[50:51] op_sel_hi:[1,0]
	v_pk_mul_f32 v[42:43], v[0:1], v[42:43]
	v_pk_mul_f32 v[40:41], v[2:3], v[40:41]
	v_pk_mul_f32 v[42:43], v[52:53], v[42:43]
	s_nop 0
	v_cvt_pk_bf16_f32 v42, v42, v43
	v_mul_f32_e32 v43, 0xbfb8aa3b, v49
	v_exp_f32_e32 v52, v43
	v_mul_f32_e32 v43, 0xbfb8aa3b, v56
	v_exp_f32_e32 v53, v43
	s_nop 0
	v_pk_add_f32 v[50:51], v[52:53], 1.0 op_sel_hi:[1,0]
	s_nop 0
	v_div_scale_f32 v43, s[2:3], v51, v51, v56
	v_rcp_f32_e32 v52, v43
	s_nop 0
	v_fma_f32 v53, -v43, v52, 1.0
	v_fmac_f32_e32 v52, v53, v52
	v_div_scale_f32 v53, vcc, v56, v51, v56
	v_mul_f32_e32 v54, v53, v52
	v_fma_f32 v55, -v43, v54, v53
	v_fmac_f32_e32 v54, v55, v52
	v_fma_f32 v43, -v43, v54, v53
	v_div_fmas_f32 v43, v43, v52, v54
	v_div_fixup_f32 v51, v43, v51, v56
	v_div_scale_f32 v43, s[2:3], v50, v50, v49
	v_rcp_f32_e32 v52, v43
	s_nop 0
	v_fma_f32 v53, -v43, v52, 1.0
	v_fmac_f32_e32 v52, v53, v52
	v_div_scale_f32 v53, vcc, v49, v50, v49
	v_mul_f32_e32 v54, v53, v52
	v_fma_f32 v55, -v43, v54, v53
	v_fmac_f32_e32 v54, v55, v52
	v_fma_f32 v43, -v43, v54, v53
	v_div_fmas_f32 v43, v43, v52, v54
	v_div_fixup_f32 v50, v43, v50, v49
	v_pk_mul_f32 v[40:41], v[50:51], v[40:41]
	s_waitcnt vmcnt(2)
; __device__ __forceinline__ unsigned pk2(float lo, float hi) { return __builtin_bit_cast(unsigned, __builtin_convertvector((f32x2p){lo, hi}, bf16x2p)); }
; __device__ __forceinline__ float shx(float v, int m, int lane) { return __builtin_bit_cast(float, __builtin_amdgcn_ds_bpermute((lane ^ m) << 2, __builtin_bit_cast(int, v))); }
; __device__ __forceinline__ float siluf(float v) { return v / (1.f + __expf(-v)); }
; __device__ __forceinline__ void gdn_out_phase(const Frame& F0, const Args& a0, int l, bool last) {
;     ...
;         for (int k = 0; k < 4; ++k) { const int ch = (F.lane + 64 * k) * 4;
;             const f32x4 o = (f32x4){bflo(oa[k].x) + bflo(ob[k].x), bfhi(oa[k].x) + bfhi(ob[k].x), bflo(oa[k].y) + bflo(ob[k].y), bfhi(oa[k].y) + bfhi(ob[k].y)};
;             float ss = (o.x * o.x + o.y * o.y) + (o.z * o.z + o.w * o.w);
; #pragma unroll
;             for (int q = 1; q < 32; q <<= 1) ss += shx(ss, q, F.lane);
;             const float rn = 1.0f / sqrtf(ss * (1.f / 128.f) + EPS);
;             const float g0 = bflo(gz[k].x), g1 = bfhi(gz[k].x), g2 = bflo(gz[k].y), g3 = bfhi(gz[k].y);
;             v2u w; w.x = pk2(o.x * rn * gn[k].x * siluf(g0), o.y * rn * gn[k].y * siluf(g1));
;             w.y = pk2(o.z * rn * gn[k].z * siluf(g2), o.w * rn * gn[k].w * siluf(g3));
;             *(v2u*)(MIX + (size_t)m * 2048 + 1024 + ch) = w; }
	v_lshlrev_b32_e32 v49, 16, v35
	v_cvt_pk_bf16_f32 v43, v40, v41
	v_lshl_add_u64 v[40:41], s[4:5], 0, v[10:11]
	global_store_dwordx2 v[40:41], v[42:43], off
	v_lshlrev_b32_e32 v40, 16, v37
	v_and_b32_e32 v41, 0xffff0000, v37
	v_lshlrev_b32_e32 v42, 16, v39
	v_and_b32_e32 v43, 0xffff0000, v39
	v_pk_add_f32 v[40:41], v[40:41], v[42:43]
	v_lshlrev_b32_e32 v42, 16, v36
	v_and_b32_e32 v43, 0xffff0000, v36
	v_lshlrev_b32_e32 v36, 16, v38
	v_and_b32_e32 v37, 0xffff0000, v38
	v_pk_add_f32 v[36:37], v[42:43], v[36:37]
	v_mov_b32_e32 v43, v41
	v_mov_b32_e32 v42, v37
	v_mov_b32_e32 v38, v36
	v_mov_b32_e32 v39, v40
	v_pk_mul_f32 v[42:43], v[42:43], v[42:43]
	v_and_b32_e32 v50, 0xffff0000, v35
	v_pk_fma_f32 v[38:39], v[38:39], v[38:39], v[42:43]
	v_lshlrev_b32_e32 v42, 16, v34
	v_add_f32_e32 v38, v38, v39
	ds_bpermute_b32 v39, v44, v38
	v_and_b32_e32 v43, 0xffff0000, v34
	v_mul_f32_e32 v34, 0xbfb8aa3b, v42
	v_mul_f32_e32 v35, 0xbfb8aa3b, v43
	v_exp_f32_e32 v34, v34
	v_exp_f32_e32 v35, v35
	s_waitcnt lgkmcnt(0)
	v_add_f32_e32 v38, v38, v39
	ds_bpermute_b32 v39, v45, v38
	v_pk_add_f32 v[34:35], v[34:35], 1.0 op_sel_hi:[1,0]
	s_nop 0
	v_div_scale_f32 v51, s[2:3], v35, v35, v43
	v_rcp_f32_e32 v52, v51
	s_waitcnt lgkmcnt(0)
	v_add_f32_e32 v38, v38, v39
	ds_bpermute_b32 v39, v46, v38
	v_fma_f32 v53, -v51, v52, 1.0
	v_fmac_f32_e32 v52, v53, v52
	v_div_scale_f32 v53, vcc, v43, v35, v43
	v_mul_f32_e32 v54, v53, v52
	v_fma_f32 v55, -v51, v54, v53
	v_fmac_f32_e32 v54, v55, v52
	s_waitcnt lgkmcnt(0)
	v_add_f32_e32 v38, v38, v39
	v_fma_f32 v51, -v51, v54, v53
	ds_bpermute_b32 v39, v47, v38
	v_div_fmas_f32 v51, v51, v52, v54
	v_div_fixup_f32 v35, v51, v35, v43
	v_div_scale_f32 v43, s[2:3], v34, v34, v42
	v_rcp_f32_e32 v51, v43
	s_waitcnt lgkmcnt(0)
	v_add_f32_e32 v38, v38, v39
	ds_bpermute_b32 v39, v48, v38
	v_fma_f32 v52, -v43, v51, 1.0
	v_fmac_f32_e32 v51, v52, v51
	v_div_scale_f32 v52, vcc, v42, v34, v42
	v_mul_f32_e32 v53, v52, v51
	v_fma_f32 v54, -v43, v53, v52
	v_fmac_f32_e32 v53, v54, v51
	s_waitcnt lgkmcnt(0)
	v_add_f32_e32 v38, v38, v39
	v_fma_f32 v43, -v43, v53, v52
	v_fmamk_f32 v38, v38, 0x3c000000, v182
	v_div_fmas_f32 v43, v43, v51, v53
	v_cmp_gt_f32_e32 vcc, s74, v38
	v_mul_f32_e32 v39, 0x4f800000, v38
	v_div_fixup_f32 v34, v43, v34, v42
	v_cndmask_b32_e32 v38, v38, v39, vcc
	v_sqrt_f32_e32 v39, v38
	s_nop 0
	v_add_u32_e32 v42, -1, v39
	v_fma_f32 v43, -v42, v39, v38
	v_cmp_ge_f32_e64 s[2:3], 0, v43
	v_add_u32_e32 v43, 1, v39
	s_nop 0
	v_cndmask_b32_e64 v42, v39, v42, s[2:3]
	v_fma_f32 v39, -v43, v39, v38
	v_cmp_lt_f32_e64 s[2:3], 0, v39
	s_nop 1
	v_cndmask_b32_e64 v39, v42, v43, s[2:3]
	v_mul_f32_e32 v42, 0x37800000, v39
	v_cndmask_b32_e32 v39, v39, v42, vcc
	v_cmp_class_f32_e32 vcc, v38, v183
	s_nop 1
	v_cndmask_b32_e32 v38, v39, v38, vcc
	v_div_scale_f32 v39, s[2:3], v38, v38, 1.0
	v_rcp_f32_e32 v42, v39
	s_nop 0
	v_fma_f32 v43, -v39, v42, 1.0
	v_fmac_f32_e32 v42, v43, v42
	v_div_scale_f32 v43, vcc, 1.0, v38, 1.0
	v_mul_f32_e32 v51, v43, v42
	v_fma_f32 v52, -v39, v51, v43
	v_fmac_f32_e32 v51, v52, v42
	v_fma_f32 v39, -v39, v51, v43
	v_div_fmas_f32 v39, v39, v42, v51
	v_div_fixup_f32 v38, v39, v38, 1.0
	v_pk_mul_f32 v[36:37], v[36:37], v[38:39] op_sel_hi:[1,0]
	v_pk_mul_f32 v[38:39], v[40:41], v[38:39] op_sel_hi:[1,0]
	v_pk_mul_f32 v[36:37], v[0:1], v[36:37]
	v_pk_mul_f32 v[38:39], v[2:3], v[38:39]
	v_pk_mul_f32 v[34:35], v[34:35], v[36:37]
	s_nop 0
	v_cvt_pk_bf16_f32 v34, v34, v35
	v_mul_f32_e32 v35, 0xbfb8aa3b, v49
	v_exp_f32_e32 v36, v35
	v_mul_f32_e32 v35, 0xbfb8aa3b, v50
	v_exp_f32_e32 v37, v35
	s_nop 0
	v_pk_add_f32 v[36:37], v[36:37], 1.0 op_sel_hi:[1,0]
	s_nop 0
	v_div_scale_f32 v35, s[2:3], v37, v37, v50
	v_rcp_f32_e32 v40, v35
	s_nop 0
	v_fma_f32 v41, -v35, v40, 1.0
	v_fmac_f32_e32 v40, v41, v40
	v_div_scale_f32 v41, vcc, v50, v37, v50
	v_mul_f32_e32 v42, v41, v40
	v_fma_f32 v43, -v35, v42, v41
	v_fmac_f32_e32 v42, v43, v40
	v_fma_f32 v35, -v35, v42, v41
	v_div_fmas_f32 v35, v35, v40, v42
	v_div_fixup_f32 v37, v35, v37, v50
	v_div_scale_f32 v35, s[2:3], v36, v36, v49
	v_rcp_f32_e32 v40, v35
	s_nop 0
	v_fma_f32 v41, -v35, v40, 1.0
	v_fmac_f32_e32 v40, v41, v40
	v_div_scale_f32 v41, vcc, v49, v36, v49
	v_mul_f32_e32 v42, v41, v40
	v_fma_f32 v43, -v35, v42, v41
	v_fmac_f32_e32 v42, v43, v40
	v_fma_f32 v35, -v35, v42, v41
	v_div_fmas_f32 v35, v35, v40, v42
	v_div_fixup_f32 v36, v35, v36, v49
	v_pk_mul_f32 v[36:37], v[36:37], v[38:39]
	s_waitcnt vmcnt(2)
	v_lshlrev_b32_e32 v38, 16, v29
	v_cvt_pk_bf16_f32 v35, v36, v37
	v_lshl_add_u64 v[36:37], s[4:5], 0, v[8:9]
	global_store_dwordx2 v[36:37], v[34:35], off
	v_lshlrev_b32_e32 v34, 16, v31
	v_and_b32_e32 v35, 0xffff0000, v31
	v_lshlrev_b32_e32 v36, 16, v33
	v_and_b32_e32 v37, 0xffff0000, v33
	v_pk_add_f32 v[34:35], v[34:35], v[36:37]
	v_lshlrev_b32_e32 v36, 16, v30
	v_and_b32_e32 v37, 0xffff0000, v30
	v_lshlrev_b32_e32 v30, 16, v32
	v_and_b32_e32 v31, 0xffff0000, v32
	v_pk_add_f32 v[30:31], v[36:37], v[30:31]
	v_mov_b32_e32 v37, v35
	v_mov_b32_e32 v36, v31
	v_mov_b32_e32 v32, v30
	v_mov_b32_e32 v33, v34
	v_pk_mul_f32 v[36:37], v[36:37], v[36:37]
	v_and_b32_e32 v39, 0xffff0000, v29
	v_pk_fma_f32 v[32:33], v[32:33], v[32:33], v[36:37]
	v_lshlrev_b32_e32 v36, 16, v28
	v_add_f32_e32 v32, v32, v33
	ds_bpermute_b32 v33, v44, v32
	v_and_b32_e32 v37, 0xffff0000, v28
	v_mul_f32_e32 v28, 0xbfb8aa3b, v36
	v_mul_f32_e32 v29, 0xbfb8aa3b, v37
	v_exp_f32_e32 v28, v28
	v_exp_f32_e32 v29, v29
	s_waitcnt lgkmcnt(0)
	v_add_f32_e32 v32, v32, v33
	ds_bpermute_b32 v33, v45, v32
	v_pk_add_f32 v[28:29], v[28:29], 1.0 op_sel_hi:[1,0]
	s_nop 0
	v_div_scale_f32 v40, s[2:3], v29, v29, v37
	v_rcp_f32_e32 v41, v40
	s_waitcnt lgkmcnt(0)
; __device__ __forceinline__ unsigned pk2(float lo, float hi) { return __builtin_bit_cast(unsigned, __builtin_convertvector((f32x2p){lo, hi}, bf16x2p)); }
; __device__ __forceinline__ float shx(float v, int m, int lane) { return __builtin_bit_cast(float, __builtin_amdgcn_ds_bpermute((lane ^ m) << 2, __builtin_bit_cast(int, v))); }
; __device__ __forceinline__ float siluf(float v) { return v / (1.f + __expf(-v)); }
; __device__ __forceinline__ void gdn_out_phase(const Frame& F0, const Args& a0, int l, bool last) {
;     ...
;         for (int k = 0; k < 4; ++k) { const int ch = (F.lane + 64 * k) * 4;
;             const f32x4 o = (f32x4){bflo(oa[k].x) + bflo(ob[k].x), bfhi(oa[k].x) + bfhi(ob[k].x), bflo(oa[k].y) + bflo(ob[k].y), bfhi(oa[k].y) + bfhi(ob[k].y)};
;             float ss = (o.x * o.x + o.y * o.y) + (o.z * o.z + o.w * o.w);
; #pragma unroll
;             for (int q = 1; q < 32; q <<= 1) ss += shx(ss, q, F.lane);
;             const float rn = 1.0f / sqrtf(ss * (1.f / 128.f) + EPS);
;             const float g0 = bflo(gz[k].x), g1 = bfhi(gz[k].x), g2 = bflo(gz[k].y), g3 = bfhi(gz[k].y);
;             v2u w; w.x = pk2(o.x * rn * gn[k].x * siluf(g0), o.y * rn * gn[k].y * siluf(g1));
;             w.y = pk2(o.z * rn * gn[k].z * siluf(g2), o.w * rn * gn[k].w * siluf(g3));
;             *(v2u*)(MIX + (size_t)m * 2048 + 1024 + ch) = w; }
	v_add_f32_e32 v32, v32, v33
	ds_bpermute_b32 v33, v46, v32
	v_fma_f32 v42, -v40, v41, 1.0
	v_fmac_f32_e32 v41, v42, v41
	v_div_scale_f32 v42, vcc, v37, v29, v37
	v_mul_f32_e32 v43, v42, v41
	v_fma_f32 v49, -v40, v43, v42
	v_fmac_f32_e32 v43, v49, v41
	s_waitcnt lgkmcnt(0)
	v_add_f32_e32 v32, v32, v33
	v_fma_f32 v40, -v40, v43, v42
	ds_bpermute_b32 v33, v47, v32
	v_div_fmas_f32 v40, v40, v41, v43
	v_div_fixup_f32 v29, v40, v29, v37
	v_div_scale_f32 v37, s[2:3], v28, v28, v36
	v_rcp_f32_e32 v40, v37
	s_waitcnt lgkmcnt(0)
	v_add_f32_e32 v32, v32, v33
	ds_bpermute_b32 v33, v48, v32
	v_fma_f32 v41, -v37, v40, 1.0
	v_fmac_f32_e32 v40, v41, v40
	v_div_scale_f32 v41, vcc, v36, v28, v36
	v_mul_f32_e32 v42, v41, v40
	v_fma_f32 v43, -v37, v42, v41
	v_fmac_f32_e32 v42, v43, v40
	s_waitcnt lgkmcnt(0)
	v_add_f32_e32 v32, v32, v33
	v_fma_f32 v37, -v37, v42, v41
	v_fmamk_f32 v32, v32, 0x3c000000, v182
	v_div_fmas_f32 v37, v37, v40, v42
	v_cmp_gt_f32_e32 vcc, s74, v32
	v_mul_f32_e32 v33, 0x4f800000, v32
	v_div_fixup_f32 v28, v37, v28, v36
	v_cndmask_b32_e32 v32, v32, v33, vcc
	v_sqrt_f32_e32 v33, v32
	s_nop 0
	v_add_u32_e32 v36, -1, v33
	v_fma_f32 v37, -v36, v33, v32
	v_cmp_ge_f32_e64 s[2:3], 0, v37
	v_add_u32_e32 v37, 1, v33
	s_nop 0
	v_cndmask_b32_e64 v36, v33, v36, s[2:3]
	v_fma_f32 v33, -v37, v33, v32
	v_cmp_lt_f32_e64 s[2:3], 0, v33
	s_nop 1
	v_cndmask_b32_e64 v33, v36, v37, s[2:3]
	v_mul_f32_e32 v36, 0x37800000, v33
	v_cndmask_b32_e32 v33, v33, v36, vcc
	v_cmp_class_f32_e32 vcc, v32, v183
	s_nop 1
	v_cndmask_b32_e32 v32, v33, v32, vcc
	v_div_scale_f32 v33, s[2:3], v32, v32, 1.0
	v_rcp_f32_e32 v36, v33
	s_nop 0
	v_fma_f32 v37, -v33, v36, 1.0
	v_fmac_f32_e32 v36, v37, v36
	v_div_scale_f32 v37, vcc, 1.0, v32, 1.0
	v_mul_f32_e32 v40, v37, v36
	v_fma_f32 v41, -v33, v40, v37
	v_fmac_f32_e32 v40, v41, v36
	v_fma_f32 v33, -v33, v40, v37
	v_div_fmas_f32 v33, v33, v36, v40
	v_div_fixup_f32 v32, v33, v32, 1.0
	v_pk_mul_f32 v[30:31], v[30:31], v[32:33] op_sel_hi:[1,0]
	v_pk_mul_f32 v[32:33], v[34:35], v[32:33] op_sel_hi:[1,0]
	v_pk_mul_f32 v[30:31], v[0:1], v[30:31]
	v_pk_mul_f32 v[32:33], v[2:3], v[32:33]
	v_pk_mul_f32 v[28:29], v[28:29], v[30:31]
	s_nop 0
	v_cvt_pk_bf16_f32 v28, v28, v29
	v_mul_f32_e32 v29, 0xbfb8aa3b, v38
	v_exp_f32_e32 v30, v29
	v_mul_f32_e32 v29, 0xbfb8aa3b, v39
	v_exp_f32_e32 v31, v29
	s_nop 0
	v_pk_add_f32 v[30:31], v[30:31], 1.0 op_sel_hi:[1,0]
	s_nop 0
	v_div_scale_f32 v29, s[2:3], v31, v31, v39
	v_rcp_f32_e32 v34, v29
	s_nop 0
	v_fma_f32 v35, -v29, v34, 1.0
	v_fmac_f32_e32 v34, v35, v34
	v_div_scale_f32 v35, vcc, v39, v31, v39
	v_mul_f32_e32 v36, v35, v34
	v_fma_f32 v37, -v29, v36, v35
	v_fmac_f32_e32 v36, v37, v34
	v_fma_f32 v29, -v29, v36, v35
	v_div_fmas_f32 v29, v29, v34, v36
	v_div_fixup_f32 v31, v29, v31, v39
	v_div_scale_f32 v29, s[2:3], v30, v30, v38
	v_rcp_f32_e32 v34, v29
	s_nop 0
	v_fma_f32 v35, -v29, v34, 1.0
	v_fmac_f32_e32 v34, v35, v34
	v_div_scale_f32 v35, vcc, v38, v30, v38
	v_mul_f32_e32 v36, v35, v34
	v_fma_f32 v37, -v29, v36, v35
	v_fmac_f32_e32 v36, v37, v34
	v_fma_f32 v29, -v29, v36, v35
	v_div_fmas_f32 v29, v29, v34, v36
	v_div_fixup_f32 v30, v29, v30, v38
	v_pk_mul_f32 v[30:31], v[30:31], v[32:33]
	s_waitcnt vmcnt(2)
	v_lshlrev_b32_e32 v32, 16, v23
	v_cvt_pk_bf16_f32 v29, v30, v31
	v_lshl_add_u64 v[30:31], s[4:5], 0, v[6:7]
	global_store_dwordx2 v[30:31], v[28:29], off
	v_lshlrev_b32_e32 v28, 16, v25
	v_and_b32_e32 v29, 0xffff0000, v25
	v_lshlrev_b32_e32 v30, 16, v27
	v_and_b32_e32 v31, 0xffff0000, v27
	v_pk_add_f32 v[28:29], v[28:29], v[30:31]
	v_lshlrev_b32_e32 v30, 16, v24
	v_and_b32_e32 v31, 0xffff0000, v24
	v_lshlrev_b32_e32 v24, 16, v26
	v_and_b32_e32 v25, 0xffff0000, v26
	v_pk_add_f32 v[24:25], v[30:31], v[24:25]
	v_mov_b32_e32 v31, v29
	v_mov_b32_e32 v30, v25
	v_mov_b32_e32 v26, v24
	v_mov_b32_e32 v27, v28
	v_pk_mul_f32 v[30:31], v[30:31], v[30:31]
	v_and_b32_e32 v33, 0xffff0000, v23
	v_pk_fma_f32 v[26:27], v[26:27], v[26:27], v[30:31]
	v_lshlrev_b32_e32 v30, 16, v22
	v_add_f32_e32 v26, v26, v27
	ds_bpermute_b32 v27, v44, v26
	v_and_b32_e32 v31, 0xffff0000, v22
	v_mul_f32_e32 v22, 0xbfb8aa3b, v30
	v_mul_f32_e32 v23, 0xbfb8aa3b, v31
	v_exp_f32_e32 v22, v22
	v_exp_f32_e32 v23, v23
	s_waitcnt lgkmcnt(0)
; __device__ __forceinline__ unsigned pk2(float lo, float hi) { return __builtin_bit_cast(unsigned, __builtin_convertvector((f32x2p){lo, hi}, bf16x2p)); }
; __device__ __forceinline__ float shx(float v, int m, int lane) { return __builtin_bit_cast(float, __builtin_amdgcn_ds_bpermute((lane ^ m) << 2, __builtin_bit_cast(int, v))); }
; __device__ __forceinline__ float siluf(float v) { return v / (1.f + __expf(-v)); }
; __device__ __forceinline__ void gdn_out_phase(const Frame& F0, const Args& a0, int l, bool last) {
;     ...
;         for (int k = 0; k < 4; ++k) { const int ch = (F.lane + 64 * k) * 4;
;             const f32x4 o = (f32x4){bflo(oa[k].x) + bflo(ob[k].x), bfhi(oa[k].x) + bfhi(ob[k].x), bflo(oa[k].y) + bflo(ob[k].y), bfhi(oa[k].y) + bfhi(ob[k].y)};
;             float ss = (o.x * o.x + o.y * o.y) + (o.z * o.z + o.w * o.w);
; #pragma unroll
;             for (int q = 1; q < 32; q <<= 1) ss += shx(ss, q, F.lane);
;             const float rn = 1.0f / sqrtf(ss * (1.f / 128.f) + EPS);
;             const float g0 = bflo(gz[k].x), g1 = bfhi(gz[k].x), g2 = bflo(gz[k].y), g3 = bfhi(gz[k].y);
;             v2u w; w.x = pk2(o.x * rn * gn[k].x * siluf(g0), o.y * rn * gn[k].y * siluf(g1));
;             w.y = pk2(o.z * rn * gn[k].z * siluf(g2), o.w * rn * gn[k].w * siluf(g3));
;             *(v2u*)(MIX + (size_t)m * 2048 + 1024 + ch) = w; }
;     }
	v_add_f32_e32 v26, v26, v27
	ds_bpermute_b32 v27, v45, v26
	v_pk_add_f32 v[22:23], v[22:23], 1.0 op_sel_hi:[1,0]
	s_nop 0
	v_div_scale_f32 v34, s[2:3], v23, v23, v31
	v_rcp_f32_e32 v35, v34
	s_waitcnt lgkmcnt(0)
	v_add_f32_e32 v26, v26, v27
	ds_bpermute_b32 v27, v46, v26
	v_fma_f32 v36, -v34, v35, 1.0
	v_fmac_f32_e32 v35, v36, v35
	v_div_scale_f32 v36, vcc, v31, v23, v31
	v_mul_f32_e32 v37, v36, v35
	v_fma_f32 v38, -v34, v37, v36
	v_fmac_f32_e32 v37, v38, v35
	s_waitcnt lgkmcnt(0)
	v_add_f32_e32 v26, v26, v27
	v_fma_f32 v34, -v34, v37, v36
	ds_bpermute_b32 v27, v47, v26
	v_div_fmas_f32 v34, v34, v35, v37
	v_div_fixup_f32 v23, v34, v23, v31
	v_div_scale_f32 v31, s[2:3], v22, v22, v30
	v_rcp_f32_e32 v34, v31
	s_waitcnt lgkmcnt(0)
	v_add_f32_e32 v26, v26, v27
	ds_bpermute_b32 v27, v48, v26
	v_fma_f32 v35, -v31, v34, 1.0
	v_fmac_f32_e32 v34, v35, v34
	v_div_scale_f32 v35, vcc, v30, v22, v30
	v_mul_f32_e32 v36, v35, v34
	v_fma_f32 v37, -v31, v36, v35
	v_fmac_f32_e32 v36, v37, v34
	s_waitcnt lgkmcnt(0)
	v_add_f32_e32 v26, v26, v27
	v_fma_f32 v31, -v31, v36, v35
	v_fmamk_f32 v26, v26, 0x3c000000, v182
	v_div_fmas_f32 v31, v31, v34, v36
	v_cmp_gt_f32_e32 vcc, s74, v26
	v_mul_f32_e32 v27, 0x4f800000, v26
	v_div_fixup_f32 v22, v31, v22, v30
	v_cndmask_b32_e32 v26, v26, v27, vcc
	v_sqrt_f32_e32 v27, v26
	s_nop 0
	v_add_u32_e32 v30, -1, v27
	v_fma_f32 v31, -v30, v27, v26
	v_cmp_ge_f32_e64 s[2:3], 0, v31
	v_add_u32_e32 v31, 1, v27
	s_nop 0
	v_cndmask_b32_e64 v30, v27, v30, s[2:3]
	v_fma_f32 v27, -v31, v27, v26
	v_cmp_lt_f32_e64 s[2:3], 0, v27
	s_nop 1
	v_cndmask_b32_e64 v27, v30, v31, s[2:3]
	v_mul_f32_e32 v30, 0x37800000, v27
	v_cndmask_b32_e32 v27, v27, v30, vcc
	v_cmp_class_f32_e32 vcc, v26, v183
	s_nop 1
	v_cndmask_b32_e32 v26, v27, v26, vcc
	v_div_scale_f32 v27, s[2:3], v26, v26, 1.0
	v_rcp_f32_e32 v30, v27
	s_nop 0
	v_fma_f32 v31, -v27, v30, 1.0
	v_fmac_f32_e32 v30, v31, v30
	v_div_scale_f32 v31, vcc, 1.0, v26, 1.0
	v_mul_f32_e32 v34, v31, v30
	v_fma_f32 v35, -v27, v34, v31
	v_fmac_f32_e32 v34, v35, v30
	v_fma_f32 v27, -v27, v34, v31
	v_div_fmas_f32 v27, v27, v30, v34
	v_div_fixup_f32 v26, v27, v26, 1.0
	v_pk_mul_f32 v[24:25], v[24:25], v[26:27] op_sel_hi:[1,0]
	v_pk_mul_f32 v[26:27], v[28:29], v[26:27] op_sel_hi:[1,0]
	v_pk_mul_f32 v[24:25], v[0:1], v[24:25]
	v_pk_mul_f32 v[26:27], v[2:3], v[26:27]
	v_pk_mul_f32 v[22:23], v[22:23], v[24:25]
	s_nop 0
	v_cvt_pk_bf16_f32 v22, v22, v23
	v_mul_f32_e32 v23, 0xbfb8aa3b, v32
	v_exp_f32_e32 v24, v23
	v_mul_f32_e32 v23, 0xbfb8aa3b, v33
	v_exp_f32_e32 v25, v23
	s_nop 0
	v_pk_add_f32 v[24:25], v[24:25], 1.0 op_sel_hi:[1,0]
	s_nop 0
	v_div_scale_f32 v23, s[2:3], v25, v25, v33
	v_rcp_f32_e32 v28, v23
	s_nop 0
	v_fma_f32 v29, -v23, v28, 1.0
	v_fmac_f32_e32 v28, v29, v28
	v_div_scale_f32 v29, vcc, v33, v25, v33
	v_mul_f32_e32 v30, v29, v28
	v_fma_f32 v31, -v23, v30, v29
	v_fmac_f32_e32 v30, v31, v28
	v_fma_f32 v23, -v23, v30, v29
	v_div_fmas_f32 v23, v23, v28, v30
	v_div_fixup_f32 v25, v23, v25, v33
	v_div_scale_f32 v23, s[2:3], v24, v24, v32
	v_rcp_f32_e32 v28, v23
	s_nop 0
	v_fma_f32 v29, -v23, v28, 1.0
	v_fmac_f32_e32 v28, v29, v28
	v_div_scale_f32 v29, vcc, v32, v24, v32
	v_mul_f32_e32 v30, v29, v28
	v_fma_f32 v31, -v23, v30, v29
	v_fmac_f32_e32 v30, v31, v28
	v_fma_f32 v23, -v23, v30, v29
	v_div_fmas_f32 v23, v23, v28, v30
	v_div_fixup_f32 v24, v23, v24, v32
	v_pk_mul_f32 v[24:25], v[24:25], v[26:27]
	s_nop 0
	v_cvt_pk_bf16_f32 v23, v24, v25
	v_lshl_add_u64 v[24:25], s[4:5], 0, v[4:5]
	global_store_dwordx2 v[24:25], v[22:23], off
	s_branch .LBB0_741

;     __device__ __forceinline__ void operator()(const f32x4 (&acc)[2][2][4][2], const Unit& u, int wr, int wc, int fr, int fq) const {
;     ...
;         const int b = u.pm / 9, r = (u.pm - 9 * b == 0) ? 4 : b;
;         const float* gate = modl + (size_t)r * 12288 + goff;
;         f32x4 gv[2][2];
; #pragma unroll
;         for (int bj = 0; bj < 2; ++bj)
; #pragma unroll
;             for (int n = 0; n < 2; ++n) gv[bj][n] = *(const f32x4*)(gate + col0 + bj * HALF + n * 16);
; #pragma unroll
;         for (int ai = 0; ai < 2; ++ai)
; #pragma unroll
;             for (int mp = 0; mp < 2; ++mp) { float* rowp = X + (size_t)(row0 + ai * HALF + mp * 32) * 2048 + col0;
;                 f32x4 xv[2][2][2];
; #pragma unroll
;                 for (int mm = 0; mm < 2; ++mm)
; #pragma unroll
;                     for (int bj = 0; bj < 2; ++bj)
; #pragma unroll
;                         for (int n = 0; n < 2; ++n) xv[mm][bj][n] = *(const f32x4*)(rowp + (size_t)mm * 16 * 2048 + bj * HALF + n * 16);
;                 __builtin_amdgcn_sched_barrier(0);
; #pragma unroll
;                 for (int mm = 0; mm < 2; ++mm)
; #pragma unroll
;                     for (int bj = 0; bj < 2; ++bj)
; #pragma unroll
;                         for (int n = 0; n < 2; ++n) *(f32x4*)(rowp + (size_t)mm * 16 * 2048 + bj * HALF + n * 16) = xv[mm][bj][n] + gv[bj][n] * acc[ai][bj][2 * mp + mm][n];
;                 __builtin_amdgcn_sched_barrier(0); }
.LBB0_838:
	s_mul_hi_i32 s12, s14, 0x38e38e39
	s_lshr_b32 s13, s12, 31
	s_ashr_i32 s12, s12, 1
	s_add_i32 s12, s12, s13
	s_mul_i32 s13, s12, -9
	s_sub_i32 s14, 0, s14
	s_cmp_lg_u32 s13, s14
	s_cselect_b32 s12, s12, 4
	s_mul_hi_i32 s13, s12, 0xc000
	s_mul_i32 s12, s12, 0xc000
	v_readlane_b32 s52, v220, 23
	v_readlane_b32 s53, v220, 24
	s_add_u32 s12, s52, s12
	s_addc_u32 s13, s53, s13
	v_lshlrev_b64 v[152:153], 2, v[128:129]
	v_lshl_add_u64 v[128:129], s[12:13], 0, v[152:153]
	s_mov_b64 s[12:13], 0x4000
	v_lshl_add_u64 v[130:131], v[128:129], 0, s[12:13]
	s_movk_i32 s12, 0x4000
	v_lshlrev_b64 v[144:145], 13, v[144:145]
	v_add_co_u32_e32 v128, vcc, s12, v128
	v_lshl_add_u64 v[144:145], s[8:9], 0, v[144:145]
	s_nop 0
	v_addc_co_u32_e32 v129, vcc, 0, v129, vcc
	v_lshl_add_u64 v[144:145], v[144:145], 0, v[152:153]
	s_mov_b32 s12, 0x20000
	v_add_co_u32_e32 v200, vcc, s12, v144
	global_load_dwordx4 v[136:139], v[130:131], off offset:64 nt
	global_load_dwordx4 v[132:135], v[130:131], off offset:512 nt
	global_load_dwordx4 v[140:143], v[128:129], off nt
	s_nop 0
	global_load_dwordx4 v[128:131], v[130:131], off offset:576 nt
	v_addc_co_u32_e32 v201, vcc, 0, v145, vcc
	global_load_dwordx4 v[152:155], v[144:145], off nt
	global_load_dwordx4 v[156:159], v[144:145], off offset:64 nt
	global_load_dwordx4 v[162:165], v[144:145], off offset:512 nt
	global_load_dwordx4 v[166:169], v[144:145], off offset:576 nt
	global_load_dwordx4 v[170:173], v[200:201], off nt
	global_load_dwordx4 v[174:177], v[200:201], off offset:64 nt
	global_load_dwordx4 v[178:181], v[200:201], off offset:512 nt
	global_load_dwordx4 v[196:199], v[200:201], off offset:576 nt
	s_waitcnt vmcnt(0)
	v_pk_fma_f32 v[106:107], v[106:107], v[130:131], v[168:169]
	v_pk_fma_f32 v[104:105], v[104:105], v[128:129], v[166:167]
	global_store_dwordx4 v[144:145], v[104:107], off offset:576
	v_pk_fma_f32 v[126:127], v[126:127], v[142:143], v[154:155]
	v_pk_fma_f32 v[124:125], v[124:125], v[140:141], v[152:153]
	v_pk_fma_f32 v[106:107], v[118:119], v[142:143], v[172:173]
	v_pk_fma_f32 v[104:105], v[116:117], v[140:141], v[170:171]
	v_pk_fma_f32 v[122:123], v[122:123], v[138:139], v[158:159]
	v_pk_fma_f32 v[120:121], v[120:121], v[136:137], v[156:157]
	v_pk_fma_f32 v[114:115], v[114:115], v[134:135], v[164:165]
	v_pk_fma_f32 v[112:113], v[112:113], v[132:133], v[162:163]
	global_store_dwordx4 v[200:201], v[104:107], off
	v_pk_fma_f32 v[102:103], v[102:103], v[134:135], v[180:181]
	v_pk_fma_f32 v[100:101], v[100:101], v[132:133], v[178:179]
	v_pk_fma_f32 v[106:107], v[110:111], v[138:139], v[176:177]
	v_pk_fma_f32 v[104:105], v[108:109], v[136:137], v[174:175]
	v_pk_fma_f32 v[98:99], v[98:99], v[130:131], v[198:199]
	v_pk_fma_f32 v[96:97], v[96:97], v[128:129], v[196:197]
	global_store_dwordx4 v[144:145], v[124:127], off
	global_store_dwordx4 v[144:145], v[120:123], off offset:64
	global_store_dwordx4 v[144:145], v[112:115], off offset:512
	global_store_dwordx4 v[200:201], v[104:107], off offset:64
	global_store_dwordx4 v[200:201], v[100:103], off offset:512
	global_store_dwordx4 v[200:201], v[96:99], off offset:576
	v_add_co_u32_e32 v154, vcc, s90, v144
	s_mov_b32 s12, 0x60000
	s_nop 0
	v_addc_co_u32_e32 v155, vcc, 0, v145, vcc
	v_add_co_u32_e32 v156, vcc, s12, v144
	v_lshl_add_u64 v[152:153], v[144:145], 0, s[88:89]
	s_nop 0
	v_addc_co_u32_e32 v157, vcc, 0, v145, vcc
	global_load_dwordx4 v[96:99], v[152:153], off offset:64 nt
	global_load_dwordx4 v[100:103], v[152:153], off offset:512 nt
	global_load_dwordx4 v[104:107], v[154:155], off nt
	global_load_dwordx4 v[108:111], v[152:153], off offset:576 nt
	global_load_dwordx4 v[112:115], v[156:157], off nt
	global_load_dwordx4 v[116:119], v[156:157], off offset:64 nt
	global_load_dwordx4 v[120:123], v[156:157], off offset:512 nt
	global_load_dwordx4 v[124:127], v[156:157], off offset:576 nt
	s_waitcnt vmcnt(4)
	v_pk_fma_f32 v[74:75], v[74:75], v[130:131], v[110:111]
	v_pk_fma_f32 v[72:73], v[72:73], v[128:129], v[108:109]
	global_store_dwordx4 v[152:153], v[72:75], off offset:576
	v_pk_fma_f32 v[94:95], v[94:95], v[142:143], v[106:107]
	v_pk_fma_f32 v[92:93], v[92:93], v[140:141], v[104:105]
	s_waitcnt vmcnt(4)
	v_pk_fma_f32 v[74:75], v[86:87], v[142:143], v[114:115]
	v_pk_fma_f32 v[72:73], v[84:85], v[140:141], v[112:113]
	v_pk_fma_f32 v[90:91], v[90:91], v[138:139], v[98:99]
	v_pk_fma_f32 v[88:89], v[88:89], v[136:137], v[96:97]
	v_pk_fma_f32 v[82:83], v[82:83], v[134:135], v[102:103]
	v_pk_fma_f32 v[80:81], v[80:81], v[132:133], v[100:101]
	global_store_dwordx4 v[156:157], v[72:75], off
	s_waitcnt vmcnt(3)
	v_pk_fma_f32 v[70:71], v[70:71], v[134:135], v[122:123]
	v_pk_fma_f32 v[68:69], v[68:69], v[132:133], v[120:121]
	v_pk_fma_f32 v[74:75], v[78:79], v[138:139], v[118:119]
	v_pk_fma_f32 v[72:73], v[76:77], v[136:137], v[116:117]
	s_waitcnt vmcnt(2)
;     __device__ __forceinline__ void operator()(const f32x4 (&acc)[2][2][4][2], const Unit& u, int wr, int wc, int fr, int fq) const {
;     ...
; #pragma unroll
;         for (int ai = 0; ai < 2; ++ai)
; #pragma unroll
;             for (int mp = 0; mp < 2; ++mp) { float* rowp = X + (size_t)(row0 + ai * HALF + mp * 32) * 2048 + col0;
;                 f32x4 xv[2][2][2];
; #pragma unroll
;                 for (int mm = 0; mm < 2; ++mm)
; #pragma unroll
;                     for (int bj = 0; bj < 2; ++bj)
; #pragma unroll
;                         for (int n = 0; n < 2; ++n) xv[mm][bj][n] = *(const f32x4*)(rowp + (size_t)mm * 16 * 2048 + bj * HALF + n * 16);
;                 __builtin_amdgcn_sched_barrier(0);
; #pragma unroll
;                 for (int mm = 0; mm < 2; ++mm)
; #pragma unroll
;                     for (int bj = 0; bj < 2; ++bj)
; #pragma unroll
;                         for (int n = 0; n < 2; ++n) *(f32x4*)(rowp + (size_t)mm * 16 * 2048 + bj * HALF + n * 16) = xv[mm][bj][n] + gv[bj][n] * acc[ai][bj][2 * mp + mm][n];
;                 __builtin_amdgcn_sched_barrier(0); }
	v_pk_fma_f32 v[66:67], v[66:67], v[130:131], v[126:127]
	v_pk_fma_f32 v[64:65], v[64:65], v[128:129], v[124:125]
	global_store_dwordx4 v[154:155], v[92:95], off
	global_store_dwordx4 v[152:153], v[88:91], off offset:64
	global_store_dwordx4 v[152:153], v[80:83], off offset:512
	global_store_dwordx4 v[156:157], v[72:75], off offset:64
	global_store_dwordx4 v[156:157], v[68:71], off offset:512
	global_store_dwordx4 v[156:157], v[64:67], off offset:576
	s_mov_b64 s[12:13], 0x100000
	v_add_co_u32_e32 v98, vcc, s73, v144
	v_lshl_add_u64 v[96:97], v[144:145], 0, s[12:13]
	s_nop 0
	v_addc_co_u32_e32 v99, vcc, 0, v145, vcc
	s_mov_b32 s12, 0x120000
	v_add_co_u32_e32 v100, vcc, s12, v144
	global_load_dwordx4 v[64:67], v[96:97], off offset:64 nt
	global_load_dwordx4 v[68:71], v[96:97], off offset:512 nt
	global_load_dwordx4 v[72:75], v[98:99], off nt
	global_load_dwordx4 v[76:79], v[96:97], off offset:576 nt
	v_addc_co_u32_e32 v101, vcc, 0, v145, vcc
	global_load_dwordx4 v[80:83], v[100:101], off nt
	global_load_dwordx4 v[84:87], v[100:101], off offset:64 nt
	global_load_dwordx4 v[88:91], v[100:101], off offset:512 nt
	global_load_dwordx4 v[92:95], v[100:101], off offset:576 nt
	s_waitcnt vmcnt(4)
	v_pk_fma_f32 v[42:43], v[42:43], v[130:131], v[78:79]
	v_pk_fma_f32 v[40:41], v[40:41], v[128:129], v[76:77]
	global_store_dwordx4 v[96:97], v[40:43], off offset:576
	v_pk_fma_f32 v[62:63], v[62:63], v[142:143], v[74:75]
	v_pk_fma_f32 v[60:61], v[60:61], v[140:141], v[72:73]
	s_waitcnt vmcnt(4)
	v_pk_fma_f32 v[42:43], v[54:55], v[142:143], v[82:83]
	v_pk_fma_f32 v[40:41], v[52:53], v[140:141], v[80:81]
	v_pk_fma_f32 v[58:59], v[58:59], v[138:139], v[66:67]
	v_pk_fma_f32 v[56:57], v[56:57], v[136:137], v[64:65]
	v_pk_fma_f32 v[50:51], v[50:51], v[134:135], v[70:71]
	v_pk_fma_f32 v[48:49], v[48:49], v[132:133], v[68:69]
	global_store_dwordx4 v[100:101], v[40:43], off
	s_waitcnt vmcnt(3)
	v_pk_fma_f32 v[38:39], v[38:39], v[134:135], v[90:91]
	v_pk_fma_f32 v[36:37], v[36:37], v[132:133], v[88:89]
	v_pk_fma_f32 v[42:43], v[46:47], v[138:139], v[86:87]
	v_pk_fma_f32 v[40:41], v[44:45], v[136:137], v[84:85]
	s_waitcnt vmcnt(2)
	v_pk_fma_f32 v[34:35], v[34:35], v[130:131], v[94:95]
	v_pk_fma_f32 v[32:33], v[32:33], v[128:129], v[92:93]
	global_store_dwordx4 v[98:99], v[60:63], off
	global_store_dwordx4 v[96:97], v[56:59], off offset:64
	global_store_dwordx4 v[96:97], v[48:51], off offset:512
	global_store_dwordx4 v[100:101], v[40:43], off offset:64
	global_store_dwordx4 v[100:101], v[36:39], off offset:512
	global_store_dwordx4 v[100:101], v[32:35], off offset:576
	s_mov_b64 s[12:13], 0x140000
	v_lshl_add_u64 v[64:65], v[144:145], 0, s[12:13]
	s_mov_b32 s12, 0x140000
	v_add_co_u32_e32 v66, vcc, s12, v144
	s_mov_b32 s12, 0x160000
	s_nop 0
	v_addc_co_u32_e32 v67, vcc, 0, v145, vcc
	v_add_co_u32_e32 v68, vcc, s12, v144
	global_load_dwordx4 v[32:35], v[64:65], off offset:64 nt
	global_load_dwordx4 v[36:39], v[64:65], off offset:512 nt
	global_load_dwordx4 v[40:43], v[66:67], off nt
	global_load_dwordx4 v[44:47], v[64:65], off offset:576 nt
	v_addc_co_u32_e32 v69, vcc, 0, v145, vcc
	global_load_dwordx4 v[48:51], v[68:69], off nt
	global_load_dwordx4 v[52:55], v[68:69], off offset:64 nt
	global_load_dwordx4 v[56:59], v[68:69], off offset:512 nt
	global_load_dwordx4 v[60:63], v[68:69], off offset:576 nt
	s_waitcnt vmcnt(4)
	v_pk_fma_f32 v[10:11], v[10:11], v[130:131], v[46:47]
	v_pk_fma_f32 v[8:9], v[8:9], v[128:129], v[44:45]
	global_store_dwordx4 v[64:65], v[8:11], off offset:576
	v_pk_fma_f32 v[30:31], v[30:31], v[142:143], v[42:43]
	v_pk_fma_f32 v[28:29], v[28:29], v[140:141], v[40:41]
	s_waitcnt vmcnt(4)
	v_pk_fma_f32 v[10:11], v[22:23], v[142:143], v[50:51]
	v_pk_fma_f32 v[8:9], v[20:21], v[140:141], v[48:49]
	v_pk_fma_f32 v[26:27], v[26:27], v[138:139], v[34:35]
	v_pk_fma_f32 v[24:25], v[24:25], v[136:137], v[32:33]
	v_pk_fma_f32 v[18:19], v[18:19], v[134:135], v[38:39]
	v_pk_fma_f32 v[16:17], v[16:17], v[132:133], v[36:37]
	global_store_dwordx4 v[68:69], v[8:11], off
	s_waitcnt vmcnt(3)
	v_pk_fma_f32 v[6:7], v[6:7], v[134:135], v[58:59]
	v_pk_fma_f32 v[4:5], v[4:5], v[132:133], v[56:57]
	v_pk_fma_f32 v[10:11], v[14:15], v[138:139], v[54:55]
	v_pk_fma_f32 v[8:9], v[12:13], v[136:137], v[52:53]
	s_waitcnt vmcnt(2)
	v_pk_fma_f32 v[2:3], v[2:3], v[130:131], v[62:63]
	v_pk_fma_f32 v[0:1], v[0:1], v[128:129], v[60:61]
	global_store_dwordx4 v[66:67], v[28:31], off
	global_store_dwordx4 v[64:65], v[24:27], off offset:64
	global_store_dwordx4 v[64:65], v[16:19], off offset:512
	global_store_dwordx4 v[68:69], v[8:11], off offset:64
	global_store_dwordx4 v[68:69], v[4:7], off offset:512
	global_store_dwordx4 v[68:69], v[0:3], off offset:576
	s_and_b64 vcc, exec, s[2:3]
	s_mov_b64 s[2:3], -1
	s_cbranch_vccnz .LBB0_813

;     __device__ __forceinline__ void operator()(const f32x4 (&acc)[2][2][4][2], const Unit& u, int wr, int wc, int fr, int fq) const {
;     ...
;         const int b = u.pm / 9, r = (u.pm - 9 * b == 0) ? 4 : b;
;         const float* gate = modl + (size_t)r * 12288 + goff;
;         f32x4 gv[2][2];
; #pragma unroll
;         for (int bj = 0; bj < 2; ++bj)
; #pragma unroll
;             for (int n = 0; n < 2; ++n) gv[bj][n] = *(const f32x4*)(gate + col0 + bj * HALF + n * 16);
; #pragma unroll
;         for (int ai = 0; ai < 2; ++ai)
; #pragma unroll
;             for (int mp = 0; mp < 2; ++mp) { float* rowp = X + (size_t)(row0 + ai * HALF + mp * 32) * 2048 + col0;
;                 f32x4 xv[2][2][2];
; #pragma unroll
;                 for (int mm = 0; mm < 2; ++mm)
; #pragma unroll
;                     for (int bj = 0; bj < 2; ++bj)
; #pragma unroll
;                         for (int n = 0; n < 2; ++n) xv[mm][bj][n] = *(const f32x4*)(rowp + (size_t)mm * 16 * 2048 + bj * HALF + n * 16);
;                 __builtin_amdgcn_sched_barrier(0);
; #pragma unroll
;                 for (int mm = 0; mm < 2; ++mm)
; #pragma unroll
;                     for (int bj = 0; bj < 2; ++bj)
; #pragma unroll
;                         for (int n = 0; n < 2; ++n) *(f32x4*)(rowp + (size_t)mm * 16 * 2048 + bj * HALF + n * 16) = xv[mm][bj][n] + gv[bj][n] * acc[ai][bj][2 * mp + mm][n];
;                 __builtin_amdgcn_sched_barrier(0); }
.LBB0_1131:
	s_mul_hi_i32 s12, s14, 0x38e38e39
	s_lshr_b32 s13, s12, 31
	s_ashr_i32 s12, s12, 1
	s_add_i32 s12, s12, s13
	s_mul_i32 s13, s12, -9
	s_sub_i32 s14, 0, s14
	s_cmp_lg_u32 s13, s14
	s_cselect_b32 s12, s12, 4
	s_mul_hi_i32 s13, s12, 0xc000
	s_mul_i32 s12, s12, 0xc000
	v_readlane_b32 s52, v220, 23
	v_readlane_b32 s53, v220, 24
	s_add_u32 s12, s52, s12
	s_addc_u32 s13, s53, s13
	v_lshlrev_b64 v[152:153], 2, v[128:129]
	v_lshl_add_u64 v[128:129], s[12:13], 0, v[152:153]
	s_mov_b64 s[12:13], 0xa000
	v_lshl_add_u64 v[130:131], v[128:129], 0, s[12:13]
	s_mov_b32 s12, 0xa000
	v_lshlrev_b64 v[144:145], 13, v[144:145]
	v_add_co_u32_e32 v128, vcc, s12, v128
	v_lshl_add_u64 v[144:145], s[8:9], 0, v[144:145]
	s_nop 0
	v_addc_co_u32_e32 v129, vcc, 0, v129, vcc
	v_lshl_add_u64 v[144:145], v[144:145], 0, v[152:153]
	s_mov_b32 s12, 0x20000
	v_add_co_u32_e32 v200, vcc, s12, v144
	global_load_dwordx4 v[136:139], v[130:131], off offset:64 nt
	global_load_dwordx4 v[132:135], v[130:131], off offset:512 nt
	global_load_dwordx4 v[140:143], v[128:129], off nt
	s_nop 0
	global_load_dwordx4 v[128:131], v[130:131], off offset:576 nt
	v_addc_co_u32_e32 v201, vcc, 0, v145, vcc
	global_load_dwordx4 v[152:155], v[144:145], off nt
	global_load_dwordx4 v[156:159], v[144:145], off offset:64 nt
	global_load_dwordx4 v[162:165], v[144:145], off offset:512 nt
	global_load_dwordx4 v[166:169], v[144:145], off offset:576 nt
	global_load_dwordx4 v[170:173], v[200:201], off nt
	global_load_dwordx4 v[174:177], v[200:201], off offset:64 nt
	global_load_dwordx4 v[178:181], v[200:201], off offset:512 nt
	global_load_dwordx4 v[196:199], v[200:201], off offset:576 nt
	s_waitcnt vmcnt(0)
	v_pk_fma_f32 v[106:107], v[106:107], v[130:131], v[168:169]
	v_pk_fma_f32 v[104:105], v[104:105], v[128:129], v[166:167]
	global_store_dwordx4 v[144:145], v[104:107], off offset:576
	v_pk_fma_f32 v[126:127], v[126:127], v[142:143], v[154:155]
	v_pk_fma_f32 v[124:125], v[124:125], v[140:141], v[152:153]
	v_pk_fma_f32 v[106:107], v[118:119], v[142:143], v[172:173]
	v_pk_fma_f32 v[104:105], v[116:117], v[140:141], v[170:171]
	v_pk_fma_f32 v[122:123], v[122:123], v[138:139], v[158:159]
	v_pk_fma_f32 v[120:121], v[120:121], v[136:137], v[156:157]
	v_pk_fma_f32 v[114:115], v[114:115], v[134:135], v[164:165]
	v_pk_fma_f32 v[112:113], v[112:113], v[132:133], v[162:163]
	global_store_dwordx4 v[200:201], v[104:107], off
	v_pk_fma_f32 v[102:103], v[102:103], v[134:135], v[180:181]
	v_pk_fma_f32 v[100:101], v[100:101], v[132:133], v[178:179]
	v_pk_fma_f32 v[106:107], v[110:111], v[138:139], v[176:177]
	v_pk_fma_f32 v[104:105], v[108:109], v[136:137], v[174:175]
	v_pk_fma_f32 v[98:99], v[98:99], v[130:131], v[198:199]
	v_pk_fma_f32 v[96:97], v[96:97], v[128:129], v[196:197]
	global_store_dwordx4 v[144:145], v[124:127], off
	global_store_dwordx4 v[144:145], v[120:123], off offset:64
	global_store_dwordx4 v[144:145], v[112:115], off offset:512
	global_store_dwordx4 v[200:201], v[104:107], off offset:64
	global_store_dwordx4 v[200:201], v[100:103], off offset:512
	global_store_dwordx4 v[200:201], v[96:99], off offset:576
	v_add_co_u32_e32 v154, vcc, s90, v144
	s_mov_b32 s12, 0x60000
	s_nop 0
	v_addc_co_u32_e32 v155, vcc, 0, v145, vcc
	v_add_co_u32_e32 v156, vcc, s12, v144
	v_lshl_add_u64 v[152:153], v[144:145], 0, s[88:89]
	s_nop 0
	v_addc_co_u32_e32 v157, vcc, 0, v145, vcc
	global_load_dwordx4 v[96:99], v[152:153], off offset:64 nt
	global_load_dwordx4 v[100:103], v[152:153], off offset:512 nt
	global_load_dwordx4 v[104:107], v[154:155], off nt
	global_load_dwordx4 v[108:111], v[152:153], off offset:576 nt
	global_load_dwordx4 v[112:115], v[156:157], off nt
	global_load_dwordx4 v[116:119], v[156:157], off offset:64 nt
	global_load_dwordx4 v[120:123], v[156:157], off offset:512 nt
	global_load_dwordx4 v[124:127], v[156:157], off offset:576 nt
	s_waitcnt vmcnt(4)
	v_pk_fma_f32 v[74:75], v[74:75], v[130:131], v[110:111]
	v_pk_fma_f32 v[72:73], v[72:73], v[128:129], v[108:109]
	global_store_dwordx4 v[152:153], v[72:75], off offset:576
	v_pk_fma_f32 v[94:95], v[94:95], v[142:143], v[106:107]
	v_pk_fma_f32 v[92:93], v[92:93], v[140:141], v[104:105]
	s_waitcnt vmcnt(4)
	v_pk_fma_f32 v[74:75], v[86:87], v[142:143], v[114:115]
	v_pk_fma_f32 v[72:73], v[84:85], v[140:141], v[112:113]
	v_pk_fma_f32 v[90:91], v[90:91], v[138:139], v[98:99]
	v_pk_fma_f32 v[88:89], v[88:89], v[136:137], v[96:97]
	v_pk_fma_f32 v[82:83], v[82:83], v[134:135], v[102:103]
	v_pk_fma_f32 v[80:81], v[80:81], v[132:133], v[100:101]
	global_store_dwordx4 v[156:157], v[72:75], off
	s_waitcnt vmcnt(3)
	v_pk_fma_f32 v[70:71], v[70:71], v[134:135], v[122:123]
	v_pk_fma_f32 v[68:69], v[68:69], v[132:133], v[120:121]
	v_pk_fma_f32 v[74:75], v[78:79], v[138:139], v[118:119]
	v_pk_fma_f32 v[72:73], v[76:77], v[136:137], v[116:117]
	s_waitcnt vmcnt(2)
;     __device__ __forceinline__ void operator()(const f32x4 (&acc)[2][2][4][2], const Unit& u, int wr, int wc, int fr, int fq) const {
;     ...
; #pragma unroll
;         for (int ai = 0; ai < 2; ++ai)
; #pragma unroll
;             for (int mp = 0; mp < 2; ++mp) { float* rowp = X + (size_t)(row0 + ai * HALF + mp * 32) * 2048 + col0;
;                 f32x4 xv[2][2][2];
; #pragma unroll
;                 for (int mm = 0; mm < 2; ++mm)
; #pragma unroll
;                     for (int bj = 0; bj < 2; ++bj)
; #pragma unroll
;                         for (int n = 0; n < 2; ++n) xv[mm][bj][n] = *(const f32x4*)(rowp + (size_t)mm * 16 * 2048 + bj * HALF + n * 16);
;                 __builtin_amdgcn_sched_barrier(0);
; #pragma unroll
;                 for (int mm = 0; mm < 2; ++mm)
; #pragma unroll
;                     for (int bj = 0; bj < 2; ++bj)
; #pragma unroll
;                         for (int n = 0; n < 2; ++n) *(f32x4*)(rowp + (size_t)mm * 16 * 2048 + bj * HALF + n * 16) = xv[mm][bj][n] + gv[bj][n] * acc[ai][bj][2 * mp + mm][n];
;                 __builtin_amdgcn_sched_barrier(0); }
	v_pk_fma_f32 v[66:67], v[66:67], v[130:131], v[126:127]
	v_pk_fma_f32 v[64:65], v[64:65], v[128:129], v[124:125]
	global_store_dwordx4 v[154:155], v[92:95], off
	global_store_dwordx4 v[152:153], v[88:91], off offset:64
	global_store_dwordx4 v[152:153], v[80:83], off offset:512
	global_store_dwordx4 v[156:157], v[72:75], off offset:64
	global_store_dwordx4 v[156:157], v[68:71], off offset:512
	global_store_dwordx4 v[156:157], v[64:67], off offset:576
	s_mov_b64 s[12:13], 0x100000
	v_add_co_u32_e32 v98, vcc, s73, v144
	v_lshl_add_u64 v[96:97], v[144:145], 0, s[12:13]
	s_nop 0
	v_addc_co_u32_e32 v99, vcc, 0, v145, vcc
	s_mov_b32 s12, 0x120000
	v_add_co_u32_e32 v100, vcc, s12, v144
	global_load_dwordx4 v[64:67], v[96:97], off offset:64 nt
	global_load_dwordx4 v[68:71], v[96:97], off offset:512 nt
	global_load_dwordx4 v[72:75], v[98:99], off nt
	global_load_dwordx4 v[76:79], v[96:97], off offset:576 nt
	v_addc_co_u32_e32 v101, vcc, 0, v145, vcc
	global_load_dwordx4 v[80:83], v[100:101], off nt
	global_load_dwordx4 v[84:87], v[100:101], off offset:64 nt
	global_load_dwordx4 v[88:91], v[100:101], off offset:512 nt
	global_load_dwordx4 v[92:95], v[100:101], off offset:576 nt
	s_waitcnt vmcnt(4)
	v_pk_fma_f32 v[42:43], v[42:43], v[130:131], v[78:79]
	v_pk_fma_f32 v[40:41], v[40:41], v[128:129], v[76:77]
	global_store_dwordx4 v[96:97], v[40:43], off offset:576
	v_pk_fma_f32 v[62:63], v[62:63], v[142:143], v[74:75]
	v_pk_fma_f32 v[60:61], v[60:61], v[140:141], v[72:73]
	s_waitcnt vmcnt(4)
	v_pk_fma_f32 v[42:43], v[54:55], v[142:143], v[82:83]
	v_pk_fma_f32 v[40:41], v[52:53], v[140:141], v[80:81]
	v_pk_fma_f32 v[58:59], v[58:59], v[138:139], v[66:67]
	v_pk_fma_f32 v[56:57], v[56:57], v[136:137], v[64:65]
	v_pk_fma_f32 v[50:51], v[50:51], v[134:135], v[70:71]
	v_pk_fma_f32 v[48:49], v[48:49], v[132:133], v[68:69]
	global_store_dwordx4 v[100:101], v[40:43], off
	s_waitcnt vmcnt(3)
	v_pk_fma_f32 v[38:39], v[38:39], v[134:135], v[90:91]
	v_pk_fma_f32 v[36:37], v[36:37], v[132:133], v[88:89]
	v_pk_fma_f32 v[42:43], v[46:47], v[138:139], v[86:87]
	v_pk_fma_f32 v[40:41], v[44:45], v[136:137], v[84:85]
	s_waitcnt vmcnt(2)
	v_pk_fma_f32 v[34:35], v[34:35], v[130:131], v[94:95]
	v_pk_fma_f32 v[32:33], v[32:33], v[128:129], v[92:93]
	global_store_dwordx4 v[98:99], v[60:63], off
	global_store_dwordx4 v[96:97], v[56:59], off offset:64
	global_store_dwordx4 v[96:97], v[48:51], off offset:512
	global_store_dwordx4 v[100:101], v[40:43], off offset:64
	global_store_dwordx4 v[100:101], v[36:39], off offset:512
	global_store_dwordx4 v[100:101], v[32:35], off offset:576
	s_mov_b64 s[12:13], 0x140000
	v_lshl_add_u64 v[64:65], v[144:145], 0, s[12:13]
	s_mov_b32 s12, 0x140000
	v_add_co_u32_e32 v66, vcc, s12, v144
	s_mov_b32 s12, 0x160000
	s_nop 0
	v_addc_co_u32_e32 v67, vcc, 0, v145, vcc
	v_add_co_u32_e32 v68, vcc, s12, v144
	global_load_dwordx4 v[32:35], v[64:65], off offset:64 nt
	global_load_dwordx4 v[36:39], v[64:65], off offset:512 nt
	global_load_dwordx4 v[40:43], v[66:67], off nt
	global_load_dwordx4 v[44:47], v[64:65], off offset:576 nt
	v_addc_co_u32_e32 v69, vcc, 0, v145, vcc
	global_load_dwordx4 v[48:51], v[68:69], off nt
	global_load_dwordx4 v[52:55], v[68:69], off offset:64 nt
	global_load_dwordx4 v[56:59], v[68:69], off offset:512 nt
	global_load_dwordx4 v[60:63], v[68:69], off offset:576 nt
	s_waitcnt vmcnt(4)
	v_pk_fma_f32 v[10:11], v[10:11], v[130:131], v[46:47]
	v_pk_fma_f32 v[8:9], v[8:9], v[128:129], v[44:45]
	global_store_dwordx4 v[64:65], v[8:11], off offset:576
	v_pk_fma_f32 v[30:31], v[30:31], v[142:143], v[42:43]
	v_pk_fma_f32 v[28:29], v[28:29], v[140:141], v[40:41]
	s_waitcnt vmcnt(4)
	v_pk_fma_f32 v[10:11], v[22:23], v[142:143], v[50:51]
	v_pk_fma_f32 v[8:9], v[20:21], v[140:141], v[48:49]
	v_pk_fma_f32 v[26:27], v[26:27], v[138:139], v[34:35]
	v_pk_fma_f32 v[24:25], v[24:25], v[136:137], v[32:33]
	v_pk_fma_f32 v[18:19], v[18:19], v[134:135], v[38:39]
	v_pk_fma_f32 v[16:17], v[16:17], v[132:133], v[36:37]
	global_store_dwordx4 v[68:69], v[8:11], off
	s_waitcnt vmcnt(3)
	v_pk_fma_f32 v[6:7], v[6:7], v[134:135], v[58:59]
	v_pk_fma_f32 v[4:5], v[4:5], v[132:133], v[56:57]
	v_pk_fma_f32 v[10:11], v[14:15], v[138:139], v[54:55]
	v_pk_fma_f32 v[8:9], v[12:13], v[136:137], v[52:53]
	s_waitcnt vmcnt(2)
	v_pk_fma_f32 v[2:3], v[2:3], v[130:131], v[62:63]
	v_pk_fma_f32 v[0:1], v[0:1], v[128:129], v[60:61]
	global_store_dwordx4 v[66:67], v[28:31], off
	global_store_dwordx4 v[64:65], v[24:27], off offset:64
	global_store_dwordx4 v[64:65], v[16:19], off offset:512
	global_store_dwordx4 v[68:69], v[8:11], off offset:64
	global_store_dwordx4 v[68:69], v[4:7], off offset:512
	global_store_dwordx4 v[68:69], v[0:3], off offset:576
	s_and_b64 vcc, exec, s[2:3]
	s_mov_b64 s[2:3], -1
	s_cbranch_vccnz .LBB0_1106

; __device__ __forceinline__ void final_norm_phase(const Frame& F0, const Args& a0) {
;     const Frame F = relaunder(F0); const Args a = relaunder_args(a0);
;     const float* X = (const float*)(a.ws + WS_X); const float* gain = a.in[I_NFINAL];
;     const int gw = F.vcu * NWAVES + F.wave, NGW = F.G * NWAVES;
;     f32x4 gn[8];
; #pragma unroll
;     for (int j = 0; j < 8; ++j) gn[j] = *(const f32x4*)(gain + (F.lane + 64 * j) * 4);
;     f32x4 v[8], vn[8];
;     int r = gw;
;     if (r < NB * SEQ) { const int b = r / SEQ, t = r - b * SEQ; const f32x4* xr = (const f32x4*)(X + ((size_t)b * TT + CTXL + t) * DM) + F.lane;
; #pragma unroll
;         for (int j = 0; j < 8; ++j) v[j] = xr[64 * j]; }
.LBB0_1184:
	s_cmp_lt_i32 s64, 38
	s_cselect_b64 s[0:1], -1, 0
	s_cmp_gt_i32 s65, 37
	s_cselect_b64 s[2:3], -1, 0
	s_and_b64 s[0:1], s[0:1], s[2:3]
	s_andn2_b64 vcc, exec, s[0:1]
	s_cbranch_vccnz .LBB0_1190
	v_readlane_b32 s0, v221, 0
	v_readlane_b32 s1, v221, 1
	v_readlane_b32 s2, v221, 2
	v_readlane_b32 s3, v221, 3
	v_readlane_b32 s4, v221, 4
	v_readlane_b32 s5, v221, 5
	v_readlane_b32 s6, v221, 6
	v_readlane_b32 s7, v221, 7
	v_readlane_b32 s8, v221, 8
	v_readlane_b32 s9, v221, 9
	v_readlane_b32 s10, v221, 10
	v_readlane_b32 s11, v221, 11
	v_readlane_b32 s12, v221, 12
	v_readlane_b32 s13, v221, 13
	v_readlane_b32 s14, v221, 14
	v_readlane_b32 s15, v221, 15
	s_waitcnt vmcnt(0)
	v_mbcnt_lo_u32_b32 v32, -1, 0
	v_mbcnt_hi_u32_b32 v32, -1, v32
	s_nop 0
	v_readlane_b32 s0, v221, 16
	v_readlane_b32 s1, v221, 17
	v_readlane_b32 s2, v221, 18
	v_readlane_b32 s3, v221, 19
	s_lshl_b32 s0, s93, 3
	s_add_i32 s2, s0, s95
	v_readlane_b32 s4, v221, 20
	v_readlane_b32 s5, v221, 21
	v_readlane_b32 s6, v221, 22
	v_readlane_b32 s7, v221, 23
	v_readlane_b32 s8, v221, 24
	v_readlane_b32 s9, v221, 25
	v_readlane_b32 s10, v221, 26
	v_readlane_b32 s11, v221, 27
	v_readlane_b32 s12, v221, 28
	v_readlane_b32 s13, v221, 29
	v_readlane_b32 s14, v221, 30
	v_readlane_b32 s15, v221, 31
	s_cmpk_lt_i32 s2, 0x2000
	s_cbranch_scc0 .LBB0_1190
	s_lshl_b32 s4, s92, 3
	s_add_u32 s0, s46, 0x18000000
	s_addc_u32 s1, s47, 0
	s_ashr_i32 s3, s2, 31
	v_lshlrev_b32_e32 v52, 2, v32
	s_lshr_b32 s5, s3, 21
	v_ashrrev_i32_e32 v53, 31, v52
	s_add_i32 s5, s2, s5
	v_lshl_add_u64 v[16:17], v[52:53], 2, s[42:43]
	s_ashr_i32 s6, s5, 11
	s_and_b32 s5, s5, 0xfffff800
	global_load_dwordx4 v[0:3], v[16:17], off nt
	global_load_dwordx4 v[4:7], v[16:17], off offset:1024 nt
	global_load_dwordx4 v[8:11], v[16:17], off offset:2048 nt
	global_load_dwordx4 v[12:15], v[16:17], off offset:3072 nt
	v_add_u32_e32 v16, 0x400, v52
	s_sub_i32 s5, s2, s5
	v_ashrrev_i32_e32 v17, 31, v16
	s_mul_hi_i32 s7, s6, 0x900
	s_mulk_i32 s6, 0x900
	s_ashr_i32 s8, s5, 31
	v_lshl_add_u64 v[24:25], v[16:17], 2, s[42:43]
	v_add_u32_e32 v16, 0x500, v52
	s_add_u32 s6, s6, s5
	v_ashrrev_i32_e32 v17, 31, v16
	s_addc_u32 s7, s7, s8
	v_lshl_add_u64 v[26:27], v[16:17], 2, s[42:43]
	global_load_dwordx4 v[16:19], v[24:25], off nt
	global_load_dwordx4 v[20:23], v[26:27], off nt
	v_add_u32_e32 v24, 0x600, v52
	s_lshl_b64 s[6:7], s[6:7], 13
	v_ashrrev_i32_e32 v25, 31, v24
	s_add_u32 s6, s0, s6
	v_ashrrev_i32_e32 v33, 31, v32
	v_lshl_add_u64 v[34:35], v[24:25], 2, s[42:43]
	v_add_u32_e32 v24, 0x700, v52
	s_addc_u32 s7, s1, s7
	v_lshlrev_b64 v[54:55], 4, v[32:33]
	v_ashrrev_i32_e32 v25, 31, v24
	v_lshl_add_u64 v[32:33], s[6:7], 0, v[54:55]
	s_mov_b64 s[6:7], 0x200000
	s_mov_b32 s5, 0x201000
	v_lshl_add_u64 v[36:37], v[24:25], 2, s[42:43]
	v_lshl_add_u64 v[56:57], v[32:33], 0, s[6:7]
	v_add_co_u32_e32 v58, vcc, s5, v32
	global_load_dwordx4 v[24:27], v[34:35], off nt
	global_load_dwordx4 v[28:31], v[36:37], off nt
	v_addc_co_u32_e32 v59, vcc, 0, v33, vcc
	global_load_dwordx4 v[88:91], v[56:57], off offset:1024 nt
	global_load_dwordx4 v[64:67], v[56:57], off offset:2048 nt
	global_load_dwordx4 v[92:95], v[58:59], off offset:-4096 nt
	global_load_dwordx4 v[48:51], v[56:57], off offset:3072 nt
	global_load_dwordx4 v[44:47], v[58:59], off nt
	global_load_dwordx4 v[40:43], v[58:59], off offset:1024 nt
	global_load_dwordx4 v[36:39], v[58:59], off offset:2048 nt
	global_load_dwordx4 v[32:35], v[58:59], off offset:3072 nt
	v_lshl_add_u64 v[96:97], s[0:1], 0, v[54:55]
	s_lshl_b64 s[0:1], s[2:3], 13
	s_add_u32 s0, s44, s0
	s_addc_u32 s1, s45, s1
	v_xor_b32_e32 v100, 4, v52
	v_xor_b32_e32 v101, 8, v52
	v_xor_b32_e32 v102, 16, v52
	v_xor_b32_e32 v103, 32, v52
	v_xor_b32_e32 v104, 64, v52
	v_xor_b32_e32 v105, 0x80, v52
	v_lshl_add_u64 v[52:53], s[0:1], 0, v[54:55]
	s_mov_b64 s[0:1], 0x1c00
	s_ashr_i32 s5, s4, 31
	s_add_i32 s3, s2, s4
	v_lshl_add_u64 v[98:99], v[52:53], 0, s[0:1]
	s_lshl_b64 s[8:9], s[4:5], 13
	s_ashr_i32 s10, s3, 31
	v_mov_b32_e32 v106, 0x358637bd
	s_mov_b32 s11, 0xf800000
	v_mov_b32_e32 v107, 0x260
	s_movk_i32 s12, 0xf000
	s_branch .LBB0_1188

; __device__ __forceinline__ void final_norm_phase(const Frame& F0, const Args& a0) {
;     ...
;     while (r < NB * SEQ) {
;         const int rn = r + NGW;
;         if (rn < NB * SEQ) { const int b = rn / SEQ, t = rn - b * SEQ; const f32x4* xr = (const f32x4*)(X + ((size_t)b * TT + CTXL + t) * DM) + F.lane;
; #pragma unroll
;             for (int j = 0; j < 8; ++j) vn[j] = xr[64 * j]; }
.LBB0_1188:
	s_cmpk_gt_i32 s3, 0x1fff
	s_cbranch_scc1 .LBB0_1187
	s_ashr_i32 s0, s3, 31
	s_lshr_b32 s0, s0, 21
	s_add_i32 s0, s3, s0
	s_ashr_i32 s1, s0, 11
	s_and_b32 s0, s0, 0xfffff800
	s_mul_hi_i32 s13, s1, 0x900
	s_mulk_i32 s1, 0x900
	s_ashr_i32 s14, s0, 31
	s_sub_u32 s0, s1, s0
	s_subb_u32 s1, s13, s14
	s_add_u32 s0, s3, s0
	s_addc_u32 s1, s10, s1
	s_lshl_b64 s[0:1], s[0:1], 13
	v_lshl_add_u64 v[72:73], v[96:97], 0, s[0:1]
	v_add_co_u32_e32 v76, vcc, 0x200000, v72
	v_lshl_add_u64 v[74:75], v[72:73], 0, s[6:7]
	s_nop 0
	v_addc_co_u32_e32 v77, vcc, 0, v73, vcc
	v_add_co_u32_e32 v108, vcc, 0x201000, v72
	global_load_dwordx4 v[56:59], v[74:75], off offset:1024 nt
	global_load_dwordx4 v[52:55], v[74:75], off offset:2048 nt
	global_load_dwordx4 v[68:71], v[76:77], off nt
	global_load_dwordx4 v[60:63], v[74:75], off offset:3072 nt
	v_addc_co_u32_e32 v109, vcc, 0, v73, vcc
	global_load_dwordx4 v[84:87], v[108:109], off nt
	global_load_dwordx4 v[80:83], v[108:109], off offset:1024 nt
	global_load_dwordx4 v[76:79], v[108:109], off offset:2048 nt
	global_load_dwordx4 v[72:75], v[108:109], off offset:3072 nt
	s_branch .LBB0_1187
